# ret_kv state-scan sequences placed XCD-consecutively (the two column halves of a head share K^T tiles in one L2)
# speedup vs baseline: 1.0054x; 1.0054x over previous
; #define LAS __attribute__((address_space(3)))
; #define PG8_STAGE(bufoff, gbase, voff) do { _Pragma("unroll") for (int _i = 0; _i < 2; ++_i) \
;         __builtin_amdgcn_global_load_lds((const unsigned*)((const char*)(gbase) + (voff)[_i]), (LAS unsigned*)(lds + (bufoff) + ldsw + _i * 8192), 16, 0, 0); } while (0)
; #define PG8_WAIT_V(n) asm volatile("s_waitcnt vmcnt(" #n ")" ::: "memory")
; #define PG8_BAR __builtin_amdgcn_s_barrier()
; template <class Epi, class Sched, bool ALIGN_EPI, bool LAST_FUSED = false, bool PERM = false, bool CARRY = false>
; __device__ __forceinline__ void gemm_phase(LAS unsigned char* lds, const int tid, const int K, const int lda, const int ldb, const Sched& S, const Epi& E) {
;     const int wid = __builtin_amdgcn_readfirstlane(tid >> 6), lane = tid & 63, wr = wid >> 2, wc = wid & 3, fr = lane & 15, fq = lane >> 4;
;     unsigned voffA[2], voffB[2];
; #pragma unroll
;     for (int i = 0; i < 2; ++i) { int Rr, C; stage_rc(tid * 16 + i * 8192, Rr, C); const int Rb = PERM ? ((Rr & ~31) + perm32(Rr & 31)) : Rr; voffA[i] = (unsigned)(Rr * lda + C) * 2u; voffB[i] = (unsigned)(Rb * ldb + C) * 2u; }
;     const size_t kstep = (size_t)(BK * 2);
;     const size_t hstepA = (size_t)HALF * lda * 2, hstepB = (size_t)HALF * ldb * 2;
;     const unsigned ldsw = (unsigned)wid * 1024u;
;     const int aoff = lds_byte(wr * 64 + fr, fq * 8), boff = lds_byte(wc * 32 + fr, fq * 8);
;     ...
;     Unit cur, nxt; int ui = 0;
;     if (!S.next(0, cur)) return;
;     f32x4 acc[2][2][4][2];
; #pragma unroll
;     for (int a = 0; a < 2; ++a)
; #pragma unroll
;         for (int b = 0; b < 2; ++b)
; #pragma unroll
;             for (int m = 0; m < 4; ++m)
; #pragma unroll
;                 for (int n = 0; n < 2; ++n) acc[a][b][m][n] = (f32x4){0.f, 0.f, 0.f, 0.f};
;     bf16x8 At[4][2], B0[2][2], B1[2][2];
;     const char* cA = cur.a; const char* cB = cur.b;
;     PG8_STAGE(PG8_SB(0, 0), cB, voffB); PG8_STAGE(PG8_SB(0, 1), cB + hstepB, voffB); PG8_STAGE(PG8_SA(0, 0), cA, voffA); PG8_STAGE(PG8_SA(0, 1), cA + hstepA, voffA);
;     if (wr == 1) PG8_BAR;
;     PG8_WAIT_V(2); PG8_BAR;
;     PG8_STAGE(PG8_SB(1, 0), cB + kstep, voffB); PG8_STAGE(PG8_SA(1, 0), cA + kstep, voffA); PG8_STAGE(PG8_SB(1, 1), cB + hstepB + kstep, voffB);
;         u.pm = ret_chunk(i, b, dir); u.pn = (((h * 2 + dir) << 1) | half); u.nt = 4; u.aux = i; map(u); return true; }
.LBB0_613:
	s_and_b64 vcc, exec, s[2:3]
	s_cbranch_vccz .LBB0_641
	s_and_b32 s98, s24, 7
	s_lshl_b32 s98, s98, 4
	s_lshr_b32 s24, s24, 3
	s_or_b32 s24, s24, s98
	s_waitcnt vmcnt(11)
	v_bfe_i32 v3, v141, 27, 1
	v_lshlrev_b32_e32 v2, 4, v141
	v_lshrrev_b32_e32 v3, 22, v3
	v_add_u32_e32 v3, v2, v3
	v_and_b32_e32 v3, 0xfffffc00, v3
	v_sub_u32_e32 v3, v2, v3
	v_lshrrev_b32_e32 v4, 4, v3
	v_ashrrev_i32_e32 v0, 31, v141
	v_bitop3_b32 v3, v4, v3, 32 bitop3:0x6c
	v_lshrrev_b32_e32 v0, 26, v0
	v_ashrrev_i32_e32 v5, 31, v3
	v_add_u32_e32 v0, v141, v0
	v_lshrrev_b32_e32 v5, 26, v5
	v_ashrrev_i32_e32 v0, 6, v0
	v_add_u32_e32 v5, v3, v5
	v_lshlrev_b32_e32 v4, 3, v0
	s_waitcnt vmcnt(10)
	v_ashrrev_i32_e32 v6, 6, v5
	v_and_b32_e32 v5, 0xc0, v5
	v_and_b32_e32 v4, -16, v4
	v_lshlrev_b32_e32 v0, 5, v0
	v_sub_u32_e32 v3, v3, v5
	v_add_u32_e32 v4, v6, v4
	v_and_b32_e32 v0, 32, v0
	v_ashrrev_i16_sdwa v3, v250, sext(v3) dst_sel:DWORD dst_unused:UNUSED_PAD src0_sel:DWORD src1_sel:BYTE_0
	v_add_u32_sdwa v0, v0, sext(v3) dst_sel:DWORD dst_unused:UNUSED_PAD src0_sel:DWORD src1_sel:WORD_0
	v_lshlrev_b32_e32 v3, 1, v4
	v_lshrrev_b32_e32 v5, 2, v4
	v_and_b32_e32 v6, 3, v6
	s_mov_b32 s2, 0x7fffe0
	s_movk_i32 s6, 0x300
	v_and_b32_e32 v3, 24, v3
	v_and_b32_e32 v5, 4, v5
	v_and_or_b32 v6, v4, s2, v6
	v_mul_lo_u32 v4, v4, s6
	v_or3_b32 v3, v6, v5, v3
	v_add_lshl_u32 v130, v0, v4, 1
	v_lshlrev_b32_e32 v0, 1, v0
	v_add_u32_e32 v2, 0x2000, v2
	v_lshl_add_u32 v0, v3, 9, v0
	v_ashrrev_i32_e32 v3, 31, v2
	v_lshrrev_b32_e32 v3, 22, v3
	v_add_u32_e32 v3, v2, v3
	v_ashrrev_i32_e32 v3, 10, v3
	v_mul_i32_i24_e32 v4, 0x400, v3
	v_sub_u32_e32 v2, v2, v4
	v_lshrrev_b32_e32 v4, 4, v2
	v_bitop3_b32 v2, v4, v2, 32 bitop3:0x6c
	v_ashrrev_i32_e32 v5, 31, v2
	v_lshrrev_b32_e32 v5, 26, v5
	v_lshlrev_b32_e32 v4, 3, v3
	v_add_u32_e32 v5, v2, v5
	v_and_b32_e32 v4, -16, v4
	v_ashrrev_i32_e32 v6, 6, v5
	s_waitcnt lgkmcnt(0)
	s_add_u32 s22, s4, 0x34b00000
	v_add_u32_e32 v4, v6, v4
	v_and_b32_e32 v6, 3, v6
	s_addc_u32 s23, s5, 0
	v_and_or_b32 v6, v4, s2, v6
	s_ashr_i32 s2, s24, 5
	s_add_i32 s18, s2, 32
	v_and_b32_e32 v5, 0xc0, v5
	s_ashr_i32 s19, s18, 31
	v_lshlrev_b32_e32 v3, 5, v3
	v_sub_u32_e32 v2, v2, v5
	s_bfe_u32 s2, s24, 0x30002
	s_lshl_b64 s[16:17], s[18:19], 3
	v_and_b32_e32 v3, 32, v3
	v_ashrrev_i16_sdwa v2, v250, sext(v2) dst_sel:DWORD dst_unused:UNUSED_PAD src0_sel:DWORD src1_sel:BYTE_0
	s_or_b32 s16, s16, s2
	s_lshl_b32 s10, s24, 8
	v_add_u32_sdwa v2, v3, sext(v2) dst_sel:DWORD dst_unused:UNUSED_PAD src0_sel:DWORD src1_sel:WORD_0
	v_lshlrev_b32_e32 v3, 1, v4
	v_lshrrev_b32_e32 v5, 2, v4
	v_mul_lo_u32 v4, v4, s6
	s_lshl_b64 s[6:7], s[16:17], 9
	s_and_b32 s33, s10, 0x100
	v_readfirstlane_b32 s12, v141
	s_or_b32 s6, s6, s33
	s_ashr_i32 s3, s12, 6
	s_mulk_i32 s7, 0x600
	s_mul_hi_u32 s10, s6, 0x600
	s_ashr_i32 s28, s12, 8
	s_lshl_b32 s29, s3, 10
	s_bfe_u32 s13, s24, 0x10001
	s_and_b32 s14, s24, 29
	s_add_i32 s7, s10, s7
	s_mulk_i32 s6, 0x600
	s_add_u32 s10, s22, s6
	s_addc_u32 s11, s23, s7
	s_cmp_eq_u32 s13, 0
	s_cselect_b64 s[6:7], -1, 0
	s_and_b64 s[26:27], s[6:7], exec
	s_mov_b32 s15, 0x29700000
	s_cselect_b32 s15, s15, 0x2bb00000
	s_add_u32 s35, s4, s15
	s_addc_u32 s44, s5, 0
	s_lshl_b64 s[4:5], s[16:17], 17
	s_add_u32 s26, s35, s4
	s_addc_u32 s27, s44, s5
	s_add_i32 s45, s29, 0
	v_and_b32_e32 v3, 24, v3
	v_and_b32_e32 v5, 4, v5
	s_add_i32 m0, s45, 0x10000
	v_or3_b32 v3, v6, v5, v3
	v_add_lshl_u32 v132, v2, v4, 1
	v_lshlrev_b32_e32 v2, 1, v2
	global_load_lds_dwordx4 v0, s[26:27]
	s_add_i32 m0, s45, 0x12000
	v_lshl_add_u32 v134, v3, 9, v2
	s_add_u32 s4, s26, 0x10000
	global_load_lds_dwordx4 v134, s[26:27]
	s_addc_u32 s5, s27, 0
	s_add_i32 m0, s45, 0x14000
	v_mov_b32_e32 v131, v1
	global_load_lds_dwordx4 v0, s[4:5]
	s_add_i32 m0, s45, 0x16000
	v_lshl_add_u64 v[2:3], s[10:11], 0, v[130:131]
	global_load_lds_dwordx4 v134, s[4:5]
	s_mov_b64 s[4:5], 0x400
	v_lshl_add_u64 v[4:5], v[2:3], 0, s[4:5]
	s_mov_b32 m0, s45
	v_mov_b32_e32 v133, v1
	global_load_lds_dwordx4 v[4:5], off
	v_lshl_add_u64 v[4:5], s[10:11], 0, v[132:133]
	s_add_i32 s50, s45, 0x2000
	v_lshl_add_u64 v[6:7], v[4:5], 0, s[4:5]
	s_add_u32 s4, s10, 0x30400
	s_mov_b32 m0, s50
	s_addc_u32 s5, s11, 0
	s_add_i32 s51, s45, 0x4000
	global_load_lds_dwordx4 v[6:7], off
	s_mov_b32 m0, s51
	s_add_i32 s52, s45, 0x6000
	global_load_lds_dwordx4 v130, s[4:5]
	s_mov_b32 m0, s52
	v_mov_b32_e32 v135, v1
	global_load_lds_dwordx4 v132, s[4:5]
	s_cmp_eq_u32 s28, 1
	v_lshl_add_u64 v[6:7], s[26:27], 0, v[0:1]
	s_cselect_b64 s[4:5], -1, 0
	s_cmp_lg_u32 s28, 1
	v_lshl_add_u64 v[8:9], s[26:27], 0, v[134:135]
	s_cbranch_scc1 .LBB0_616
	s_barrier
